# LayerNorm loop heads (LN1, LN2): 32 row loads issued back to back, partial row sums after one wait (two exposed round trips per iteration removed)
# speedup vs baseline: 1.0175x; 1.0010x over previous
.LBB0_1223:
	v_add_co_u32_e32 v0, vcc, 0xffff8400, v140
	s_add_u32 s13, s8, s14
	s_nop 0
	v_addc_co_u32_e32 v1, vcc, -1, v141, vcc
	v_add_co_u32_e32 v2, vcc, 0xffff8800, v140
	s_addc_u32 s11, s9, s15
	s_nop 0
	v_addc_co_u32_e32 v3, vcc, -1, v141, vcc
	global_load_dwordx4 v[104:107], v[0:1], off nt
	s_nop 1
	global_load_dwordx4 v[64:67], v[2:3], off nt
	v_add_co_u32_e32 v0, vcc, 0xffff8c00, v140
	s_nop 1
	s_nop 1
	v_addc_co_u32_e32 v1, vcc, -1, v141, vcc
	v_add_co_u32_e32 v2, vcc, 0xffff9000, v140
	s_nop 1
	s_nop 0
	v_addc_co_u32_e32 v3, vcc, -1, v141, vcc
	v_add_co_u32_e32 v4, vcc, 0xffff9400, v140
	global_load_dwordx4 v[32:35], v[0:1], off nt
	s_nop 0
	global_load_dwordx4 v[0:3], v[2:3], off nt
	v_addc_co_u32_e32 v5, vcc, -1, v141, vcc
	v_add_co_u32_e32 v6, vcc, 0xffff9800, v140
	s_nop 1
	s_nop 0
	v_addc_co_u32_e32 v7, vcc, -1, v141, vcc
	global_load_dwordx4 v[96:99], v[4:5], off nt
	global_load_dwordx4 v[68:71], v[6:7], off nt
	v_add_co_u32_e32 v4, vcc, 0xffff9c00, v140
	s_nop 1
	s_nop 1
	v_addc_co_u32_e32 v5, vcc, -1, v141, vcc
	v_add_co_u32_e32 v6, vcc, 0xffffa000, v140
	s_nop 1
	s_nop 0
	v_addc_co_u32_e32 v7, vcc, -1, v141, vcc
	v_add_co_u32_e32 v8, vcc, 0xffffa400, v140
	global_load_dwordx4 v[36:39], v[4:5], off nt
	s_nop 0
	global_load_dwordx4 v[4:7], v[6:7], off nt
	v_addc_co_u32_e32 v9, vcc, -1, v141, vcc
	v_add_co_u32_e32 v10, vcc, 0xffffa800, v140
	s_nop 1
	s_nop 0
	v_addc_co_u32_e32 v11, vcc, -1, v141, vcc
	global_load_dwordx4 v[108:111], v[8:9], off nt
	global_load_dwordx4 v[72:75], v[10:11], off nt
	v_add_co_u32_e32 v8, vcc, 0xffffac00, v140
	s_nop 1
	s_nop 0
	v_addc_co_u32_e32 v9, vcc, -1, v141, vcc
	v_add_co_u32_e32 v10, vcc, 0xffffb000, v140
	s_nop 1
	s_nop 0
	v_addc_co_u32_e32 v11, vcc, -1, v141, vcc
	v_add_co_u32_e32 v12, vcc, 0xffffb400, v140
	global_load_dwordx4 v[40:43], v[8:9], off nt
	s_nop 0
	global_load_dwordx4 v[8:11], v[10:11], off nt
	v_addc_co_u32_e32 v13, vcc, -1, v141, vcc
	v_add_co_u32_e32 v14, vcc, 0xffffb800, v140
	s_nop 1
	s_nop 1
	v_addc_co_u32_e32 v15, vcc, -1, v141, vcc
	global_load_dwordx4 v[100:103], v[12:13], off nt
	global_load_dwordx4 v[76:79], v[14:15], off nt
	v_add_co_u32_e32 v12, vcc, 0xffffbc00, v140
	s_nop 1
	s_nop 0
	v_addc_co_u32_e32 v13, vcc, -1, v141, vcc
	v_add_co_u32_e32 v14, vcc, 0xffffc000, v140
	s_nop 1
	s_nop 0
	v_addc_co_u32_e32 v15, vcc, -1, v141, vcc
	v_add_co_u32_e32 v16, vcc, 0xffffc400, v140
	global_load_dwordx4 v[44:47], v[12:13], off nt
	s_nop 0
	global_load_dwordx4 v[12:15], v[14:15], off nt
	v_addc_co_u32_e32 v17, vcc, -1, v141, vcc
	v_add_co_u32_e32 v18, vcc, 0xffffc800, v140
	s_nop 1
	s_nop 0
	v_addc_co_u32_e32 v19, vcc, -1, v141, vcc
	global_load_dwordx4 v[116:119], v[16:17], off nt
	global_load_dwordx4 v[80:83], v[18:19], off nt
	v_add_co_u32_e32 v16, vcc, 0xffffcc00, v140
	s_nop 1
	s_nop 0
	v_addc_co_u32_e32 v17, vcc, -1, v141, vcc
	v_add_co_u32_e32 v18, vcc, 0xffffd000, v140
	s_nop 1
	s_nop 0
	v_addc_co_u32_e32 v19, vcc, -1, v141, vcc
	v_add_co_u32_e32 v20, vcc, 0xffffd400, v140
	global_load_dwordx4 v[48:51], v[16:17], off nt
	s_nop 0
	global_load_dwordx4 v[16:19], v[18:19], off nt
	v_addc_co_u32_e32 v21, vcc, -1, v141, vcc
	v_add_co_u32_e32 v22, vcc, 0xffffd800, v140
	s_nop 1
	s_nop 0
	v_addc_co_u32_e32 v23, vcc, -1, v141, vcc
	global_load_dwordx4 v[112:115], v[20:21], off nt
	global_load_dwordx4 v[84:87], v[22:23], off nt
	v_add_co_u32_e32 v20, vcc, 0xffffdc00, v140
	s_nop 1
	s_nop 0
	v_addc_co_u32_e32 v21, vcc, -1, v141, vcc
	v_add_co_u32_e32 v22, vcc, 0xffffe000, v140
	s_nop 1
	s_nop 0
	v_addc_co_u32_e32 v23, vcc, -1, v141, vcc
	v_add_co_u32_e32 v24, vcc, 0xffffe400, v140
	global_load_dwordx4 v[52:55], v[20:21], off nt
	s_nop 0
	global_load_dwordx4 v[20:23], v[22:23], off nt
	v_addc_co_u32_e32 v25, vcc, -1, v141, vcc
	v_add_co_u32_e32 v26, vcc, s46, v140
	s_nop 1
	s_nop 0
	v_addc_co_u32_e32 v27, vcc, -1, v141, vcc
	global_load_dwordx4 v[124:127], v[24:25], off nt
	global_load_dwordx4 v[88:91], v[26:27], off nt
	v_add_co_u32_e32 v24, vcc, 0xffffec00, v140
	s_nop 1
	s_nop 0
	v_addc_co_u32_e32 v25, vcc, -1, v141, vcc
	v_add_co_u32_e32 v26, vcc, 0xfffff000, v140
	s_nop 1
	s_nop 0
	v_addc_co_u32_e32 v27, vcc, -1, v141, vcc
	global_load_dwordx4 v[56:59], v[24:25], off nt
	s_nop 0
	global_load_dwordx4 v[24:27], v[26:27], off nt
	v_add_co_u32_e32 v28, vcc, 0xfffff400, v140
	s_nop 1
	s_nop 0
	v_addc_co_u32_e32 v29, vcc, -1, v141, vcc
	v_add_co_u32_e32 v30, vcc, 0xfffff800, v140
	s_nop 1
	s_nop 0
	v_addc_co_u32_e32 v31, vcc, -1, v141, vcc
	global_load_dwordx4 v[120:123], v[28:29], off nt
	global_load_dwordx4 v[92:95], v[30:31], off nt
	v_add_co_u32_e32 v28, vcc, s76, v140
	s_nop 1
	s_nop 0
	v_addc_co_u32_e32 v29, vcc, -1, v141, vcc
	global_load_dwordx4 v[60:63], v[28:29], off nt
	s_nop 0
	global_load_dwordx4 v[28:31], v[140:141], off nt
	s_waitcnt vmcnt(0) lgkmcnt(0)
	v_add_f32_e32 v128, v104, v105
	v_add_f32_e32 v129, v106, v107
	v_add_f32_e32 v128, v128, v129
	v_add_f32_e32 v129, v64, v65
	v_add_f32_e32 v130, v66, v67
	v_add_f32_e32 v128, 0, v128
	v_add_f32_e32 v129, v129, v130
	v_add_f32_e32 v128, v128, v129
	v_add_f32_e32 v129, v32, v33
	v_add_f32_e32 v130, v34, v35
	v_add_f32_e32 v129, v129, v130
	v_add_f32_e32 v128, v128, v129
	v_add_f32_e32 v129, v0, v1
	v_add_f32_e32 v130, v2, v3
	v_add_f32_e32 v129, v129, v130
	v_add_f32_e32 v128, v128, v129
	v_add_f32_e32 v129, v96, v97
	v_add_f32_e32 v130, v98, v99
	v_add_f32_e32 v129, v129, v130
	v_add_f32_e32 v130, v68, v69
	v_add_f32_e32 v131, v70, v71
	v_add_f32_e32 v129, 0, v129
	v_add_f32_e32 v130, v130, v131
	v_add_f32_e32 v129, v129, v130
	s_waitcnt vmcnt(0)
	v_add_f32_e32 v130, v36, v37
	v_add_f32_e32 v131, v38, v39
	v_add_f32_e32 v130, v130, v131
	v_add_f32_e32 v129, v129, v130
	v_add_f32_e32 v130, v4, v5
	v_add_f32_e32 v131, v6, v7
	v_add_f32_e32 v130, v130, v131
	v_add_f32_e32 v129, v129, v130
	v_add_f32_e32 v130, v108, v109
	v_add_f32_e32 v131, v110, v111
	v_add_f32_e32 v130, v130, v131
	v_add_f32_e32 v131, v72, v73
	v_add_f32_e32 v132, v74, v75
	v_add_f32_e32 v130, 0, v130
	v_add_f32_e32 v131, v131, v132
	v_add_f32_e32 v130, v130, v131
	v_add_f32_e32 v131, v40, v41
	v_add_f32_e32 v132, v42, v43
	v_add_f32_e32 v131, v131, v132
	v_add_f32_e32 v130, v130, v131
	v_add_f32_e32 v131, v8, v9
	v_add_f32_e32 v132, v10, v11
	v_add_f32_e32 v131, v131, v132
	v_add_f32_e32 v130, v130, v131
	s_waitcnt lgkmcnt(0)
	v_add_f32_e32 v131, v100, v101
	v_add_f32_e32 v132, v102, v103
	v_add_f32_e32 v131, v131, v132
	v_add_f32_e32 v132, v76, v77
	v_add_f32_e32 v133, v78, v79
	v_add_f32_e32 v131, 0, v131
	v_add_f32_e32 v132, v132, v133
	v_add_f32_e32 v131, v131, v132
	v_add_f32_e32 v132, v44, v45
	v_add_f32_e32 v133, v46, v47
	v_add_f32_e32 v132, v132, v133
	v_add_f32_e32 v131, v131, v132
	v_add_f32_e32 v132, v12, v13
	v_add_f32_e32 v133, v14, v15
	v_add_f32_e32 v132, v132, v133
	v_add_f32_e32 v131, v131, v132
	v_add_f32_e32 v132, v116, v117
	v_add_f32_e32 v133, v118, v119
	v_add_f32_e32 v132, v132, v133
	v_add_f32_e32 v133, v80, v81
	v_add_f32_e32 v142, v82, v83
	v_add_f32_e32 v132, 0, v132
	v_add_f32_e32 v133, v133, v142
	v_add_f32_e32 v132, v132, v133
	v_add_f32_e32 v133, v48, v49
	v_add_f32_e32 v142, v50, v51
	v_add_f32_e32 v133, v133, v142
	v_add_f32_e32 v132, v132, v133
	v_add_f32_e32 v133, v16, v17
	v_add_f32_e32 v142, v18, v19
	v_add_f32_e32 v133, v133, v142
	v_add_f32_e32 v132, v132, v133
	v_add_f32_e32 v133, v112, v113
	v_add_f32_e32 v142, v114, v115
	v_add_f32_e32 v133, v133, v142
	v_add_f32_e32 v142, v84, v85
	v_add_f32_e32 v143, v86, v87
	v_add_f32_e32 v133, 0, v133
	v_add_f32_e32 v142, v142, v143
	v_add_f32_e32 v133, v133, v142
	v_add_f32_e32 v142, v52, v53
	v_add_f32_e32 v143, v54, v55
	v_add_f32_e32 v142, v142, v143
	v_add_f32_e32 v133, v133, v142
	v_add_f32_e32 v142, v20, v21
	v_add_f32_e32 v143, v22, v23
	v_add_f32_e32 v142, v142, v143
	v_add_f32_e32 v142, v133, v142
	v_add_f32_e32 v133, v124, v125
	v_add_f32_e32 v143, v126, v127
	v_add_f32_e32 v133, v133, v143
	v_add_f32_e32 v143, v88, v89
	v_add_f32_e32 v144, v90, v91
	v_add_f32_e32 v133, 0, v133
	v_add_f32_e32 v143, v143, v144
	v_add_f32_e32 v133, v133, v143
	v_add_f32_e32 v143, v56, v57
	v_add_f32_e32 v144, v58, v59
	v_add_f32_e32 v143, v143, v144
	v_add_f32_e32 v133, v133, v143
	v_add_f32_e32 v143, v24, v25
	v_add_f32_e32 v144, v26, v27
	v_add_f32_e32 v143, v143, v144
	v_add_f32_e32 v143, v133, v143
	v_add_f32_e32 v133, v120, v121
	v_add_f32_e32 v144, v122, v123
	v_add_f32_e32 v133, v133, v144
	ds_swizzle_b32 v144, v128 offset:swizzle(SWAP,1)
	v_add_f32_e32 v145, v92, v93
	v_add_f32_e32 v146, v94, v95
	v_add_f32_e32 v133, 0, v133
	v_add_f32_e32 v145, v145, v146
	s_waitcnt lgkmcnt(0)
	v_add_f32_e32 v128, v128, v144
	v_add_f32_e32 v133, v133, v145
	ds_swizzle_b32 v145, v129 offset:swizzle(SWAP,1)
	ds_swizzle_b32 v144, v128 offset:swizzle(SWAP,2)
	v_add_f32_e32 v146, v60, v61
	v_add_f32_e32 v147, v62, v63
	v_add_f32_e32 v146, v146, v147
	s_waitcnt lgkmcnt(1)
	v_add_f32_e32 v129, v129, v145
	s_waitcnt lgkmcnt(0)
	v_add_f32_e32 v128, v128, v144
	ds_swizzle_b32 v145, v129 offset:swizzle(SWAP,2)
	ds_swizzle_b32 v144, v128 offset:swizzle(SWAP,4)
	v_add_f32_e32 v133, v133, v146
	v_add_f32_e32 v146, v28, v29
	v_add_f32_e32 v147, v30, v31
	s_waitcnt lgkmcnt(1)
	v_add_f32_e32 v129, v129, v145
	s_waitcnt lgkmcnt(0)
	v_add_f32_e32 v128, v128, v144
	ds_swizzle_b32 v145, v129 offset:swizzle(SWAP,4)
	ds_swizzle_b32 v144, v128 offset:swizzle(SWAP,8)
	v_add_f32_e32 v146, v146, v147
	v_add_f32_e32 v146, v133, v146
	s_waitcnt lgkmcnt(1)
	v_add_f32_e32 v129, v129, v145
	s_waitcnt lgkmcnt(0)
	v_add_f32_e32 v128, v128, v144
	ds_swizzle_b32 v145, v129 offset:swizzle(SWAP,8)
	ds_swizzle_b32 v144, v128 offset:swizzle(SWAP,16)
	s_waitcnt lgkmcnt(1)
	v_add_f32_e32 v129, v129, v145
	s_waitcnt lgkmcnt(0)
	v_add_f32_e32 v128, v128, v144
	ds_swizzle_b32 v144, v129 offset:swizzle(SWAP,16)
	ds_swizzle_b32 v145, v130 offset:swizzle(SWAP,1)
	v_mov_b32_e32 v133, v128
	s_nop 1
	v_permlane32_swap_b32_e32 v128, v133
	v_add_f32_e32 v165, v128, v133
	s_waitcnt lgkmcnt(1)
	v_add_f32_e32 v128, v129, v144
	ds_swizzle_b32 v144, v131 offset:swizzle(SWAP,1)
	s_waitcnt lgkmcnt(1)
	v_add_f32_e32 v129, v130, v145
	ds_swizzle_b32 v130, v129 offset:swizzle(SWAP,2)
	v_mov_b32_e32 v133, v128
	s_nop 1
	v_permlane32_swap_b32_e32 v128, v133
	s_waitcnt lgkmcnt(1)
	v_add_f32_e32 v131, v131, v144
	ds_swizzle_b32 v144, v131 offset:swizzle(SWAP,2)
	v_add_f32_e32 v164, v128, v133
	ds_swizzle_b32 v128, v132 offset:swizzle(SWAP,1)
	s_waitcnt lgkmcnt(2)
	v_add_f32_e32 v129, v129, v130
	ds_swizzle_b32 v130, v129 offset:swizzle(SWAP,4)
	s_waitcnt lgkmcnt(2)
	v_add_f32_e32 v131, v131, v144
	ds_swizzle_b32 v133, v131 offset:swizzle(SWAP,4)
	s_waitcnt lgkmcnt(2)
	v_add_f32_e32 v128, v132, v128
	ds_swizzle_b32 v132, v128 offset:swizzle(SWAP,2)
	s_waitcnt lgkmcnt(2)
	v_add_f32_e32 v129, v129, v130
	ds_swizzle_b32 v130, v129 offset:swizzle(SWAP,8)
	s_waitcnt lgkmcnt(2)
	v_add_f32_e32 v131, v131, v133
	ds_swizzle_b32 v133, v131 offset:swizzle(SWAP,8)
	s_waitcnt lgkmcnt(2)
	v_add_f32_e32 v128, v128, v132
	ds_swizzle_b32 v132, v128 offset:swizzle(SWAP,4)
	s_waitcnt lgkmcnt(2)
	v_add_f32_e32 v129, v129, v130
	ds_swizzle_b32 v130, v129 offset:swizzle(SWAP,16)
	s_waitcnt lgkmcnt(2)
	v_add_f32_e32 v131, v131, v133
	ds_swizzle_b32 v144, v131 offset:swizzle(SWAP,16)
	s_waitcnt lgkmcnt(2)
	v_add_f32_e32 v128, v128, v132
	ds_swizzle_b32 v132, v128 offset:swizzle(SWAP,8)
	s_waitcnt lgkmcnt(2)
	v_add_f32_e32 v129, v129, v130
	v_mov_b32_e32 v130, v129
	s_nop 1
	v_permlane32_swap_b32_e32 v129, v130
	v_add_f32_e32 v133, v129, v130
	s_waitcnt lgkmcnt(1)
	v_add_f32_e32 v129, v131, v144
	ds_swizzle_b32 v144, v142 offset:swizzle(SWAP,1)
	s_waitcnt lgkmcnt(1)
	v_add_f32_e32 v128, v128, v132
	ds_swizzle_b32 v131, v128 offset:swizzle(SWAP,16)
	v_mov_b32_e32 v130, v129
	s_nop 1
	v_permlane32_swap_b32_e32 v129, v130
	v_add_f32_e32 v132, v129, v130
	s_waitcnt lgkmcnt(1)
	v_add_f32_e32 v129, v142, v144
	ds_swizzle_b32 v142, v143 offset:swizzle(SWAP,1)
	s_waitcnt lgkmcnt(1)
	v_add_f32_e32 v128, v128, v131
	ds_swizzle_b32 v130, v129 offset:swizzle(SWAP,2)
	v_mov_b32_e32 v131, v128
	s_nop 1
	v_permlane32_swap_b32_e32 v128, v131
	s_waitcnt lgkmcnt(1)
	v_add_f32_e32 v142, v143, v142
	v_add_f32_e32 v131, v128, v131
	ds_swizzle_b32 v128, v146 offset:swizzle(SWAP,1)
	ds_swizzle_b32 v143, v142 offset:swizzle(SWAP,2)
	s_waitcnt lgkmcnt(2)
	v_add_f32_e32 v129, v129, v130
	ds_swizzle_b32 v130, v129 offset:swizzle(SWAP,4)
	v_fmamk_f32 v151, v165, 0xba800000, v107
	s_waitcnt lgkmcnt(2)
	v_add_f32_e32 v128, v146, v128
	s_waitcnt lgkmcnt(1)
	v_add_f32_e32 v142, v142, v143
	ds_swizzle_b32 v144, v128 offset:swizzle(SWAP,2)
	ds_swizzle_b32 v143, v142 offset:swizzle(SWAP,4)
	s_waitcnt lgkmcnt(2)
	v_add_f32_e32 v129, v129, v130
	ds_swizzle_b32 v130, v129 offset:swizzle(SWAP,8)
	v_fmamk_f32 v105, v165, 0xba800000, v105
	s_waitcnt lgkmcnt(2)
	v_add_f32_e32 v128, v128, v144
	s_waitcnt lgkmcnt(1)
	v_add_f32_e32 v142, v142, v143
	ds_swizzle_b32 v144, v128 offset:swizzle(SWAP,4)
	ds_swizzle_b32 v143, v142 offset:swizzle(SWAP,8)
	s_waitcnt lgkmcnt(2)
	v_add_f32_e32 v129, v129, v130
	ds_swizzle_b32 v130, v129 offset:swizzle(SWAP,16)
	v_fmamk_f32 v150, v165, 0xba800000, v106
	s_waitcnt lgkmcnt(2)
	v_add_f32_e32 v128, v128, v144
	s_waitcnt lgkmcnt(1)
	v_add_f32_e32 v142, v142, v143
	ds_swizzle_b32 v144, v128 offset:swizzle(SWAP,8)
	ds_swizzle_b32 v143, v142 offset:swizzle(SWAP,16)
	s_waitcnt lgkmcnt(2)
	v_add_f32_e32 v129, v129, v130
	v_mov_b32_e32 v130, v129
	s_nop 1
	v_permlane32_swap_b32_e32 v129, v130
	s_waitcnt lgkmcnt(1)
	v_add_f32_e32 v128, v128, v144
	v_add_f32_e32 v130, v129, v130
	s_waitcnt lgkmcnt(0)
	v_add_f32_e32 v129, v142, v143
	ds_swizzle_b32 v142, v128 offset:swizzle(SWAP,16)
	v_fmac_f32_e32 v104, 0xba800000, v165
	v_mul_f32_e32 v106, v105, v105
	v_mul_f32_e32 v107, v151, v151
	v_fmac_f32_e32 v106, v104, v104
	s_waitcnt lgkmcnt(0)
	v_add_f32_e32 v128, v128, v142
	v_mov_b32_e32 v142, v128
	s_nop 1
	v_permlane32_swap_b32_e32 v128, v142
	v_fmac_f32_e32 v107, v150, v150
	v_fmamk_f32 v67, v165, 0xba800000, v67
	v_fmamk_f32 v65, v165, 0xba800000, v65
	v_add_f32_e32 v128, v128, v142
	v_add_f32_e32 v106, v106, v107
	v_fmamk_f32 v66, v165, 0xba800000, v66
	v_fmac_f32_e32 v64, 0xba800000, v165
	v_mul_f32_e32 v107, v65, v65
	v_mul_f32_e32 v142, v67, v67
	v_fmac_f32_e32 v107, v64, v64
	v_fmac_f32_e32 v142, v66, v66
	v_add_f32_e32 v107, v107, v142
	v_fmamk_f32 v35, v165, 0xba800000, v35
	v_fmamk_f32 v33, v165, 0xba800000, v33
	v_add_f32_e32 v106, v106, v107
	v_fmamk_f32 v34, v165, 0xba800000, v34
	v_fmac_f32_e32 v32, 0xba800000, v165
	v_mul_f32_e32 v107, v33, v33
	v_mul_f32_e32 v142, v35, v35
	v_fmac_f32_e32 v107, v32, v32
	v_fmac_f32_e32 v142, v34, v34
	v_add_f32_e32 v107, v107, v142
	v_fmamk_f32 v3, v165, 0xba800000, v3
	v_fmamk_f32 v1, v165, 0xba800000, v1
	v_add_f32_e32 v106, v107, v106
	v_fmamk_f32 v2, v165, 0xba800000, v2
	v_fmac_f32_e32 v0, 0xba800000, v165
	v_mul_f32_e32 v107, v1, v1
	v_mul_f32_e32 v142, v3, v3
	v_fmac_f32_e32 v107, v0, v0
	v_fmac_f32_e32 v142, v2, v2
	v_add_f32_e32 v107, v107, v142
	v_fmamk_f32 v99, v164, 0xba800000, v99
	v_fmamk_f32 v97, v164, 0xba800000, v97
	v_add_f32_e32 v166, v107, v106
	v_fmamk_f32 v98, v164, 0xba800000, v98
	v_fmac_f32_e32 v96, 0xba800000, v164
	v_mul_f32_e32 v106, v97, v97
	v_mul_f32_e32 v107, v99, v99
	v_fmac_f32_e32 v106, v96, v96
	v_fmac_f32_e32 v107, v98, v98
	v_add_f32_e32 v142, v106, v107
	v_fmamk_f32 v107, v164, 0xba800000, v71
	v_fmamk_f32 v69, v164, 0xba800000, v69
	v_fmamk_f32 v106, v164, 0xba800000, v70
	v_fmac_f32_e32 v68, 0xba800000, v164
	v_mul_f32_e32 v70, v69, v69
	v_mul_f32_e32 v71, v107, v107
	v_fmac_f32_e32 v70, v68, v68
	v_fmac_f32_e32 v71, v106, v106
	v_add_f32_e32 v70, v70, v71
	v_fmamk_f32 v39, v164, 0xba800000, v39
	v_fmamk_f32 v37, v164, 0xba800000, v37
	v_add_f32_e32 v70, v142, v70
	v_fmamk_f32 v38, v164, 0xba800000, v38
	v_fmac_f32_e32 v36, 0xba800000, v164
	v_mul_f32_e32 v71, v37, v37
	v_mul_f32_e32 v142, v39, v39
	v_fmac_f32_e32 v71, v36, v36
	v_fmac_f32_e32 v142, v38, v38
	v_add_f32_e32 v71, v71, v142
	v_fmamk_f32 v7, v164, 0xba800000, v7
	v_fmamk_f32 v5, v164, 0xba800000, v5
	v_add_f32_e32 v70, v71, v70
	v_fmamk_f32 v6, v164, 0xba800000, v6
	v_fmac_f32_e32 v4, 0xba800000, v164
	v_mul_f32_e32 v71, v5, v5
	v_mul_f32_e32 v142, v7, v7
	v_fmac_f32_e32 v71, v4, v4
	v_fmac_f32_e32 v142, v6, v6
	v_add_f32_e32 v71, v71, v142
	v_fmamk_f32 v153, v133, 0xba800000, v111
	v_fmamk_f32 v109, v133, 0xba800000, v109
	v_add_f32_e32 v167, v71, v70
	v_fmamk_f32 v152, v133, 0xba800000, v110
	v_fmac_f32_e32 v108, 0xba800000, v133
	v_mul_f32_e32 v70, v109, v109
	v_mul_f32_e32 v71, v153, v153
	v_fmac_f32_e32 v70, v108, v108
	v_fmac_f32_e32 v71, v152, v152
	v_fmamk_f32 v111, v133, 0xba800000, v75
	v_fmamk_f32 v73, v133, 0xba800000, v73
	v_add_f32_e32 v70, v70, v71
	v_fmamk_f32 v110, v133, 0xba800000, v74
	v_fmac_f32_e32 v72, 0xba800000, v133
	v_mul_f32_e32 v71, v73, v73
	v_mul_f32_e32 v74, v111, v111
	v_fmac_f32_e32 v71, v72, v72
	v_fmac_f32_e32 v74, v110, v110
	v_add_f32_e32 v71, v71, v74
	v_fmamk_f32 v43, v133, 0xba800000, v43
	v_fmamk_f32 v41, v133, 0xba800000, v41
	v_add_f32_e32 v70, v70, v71
	v_fmamk_f32 v42, v133, 0xba800000, v42
	v_fmac_f32_e32 v40, 0xba800000, v133
	v_mul_f32_e32 v71, v41, v41
	v_mul_f32_e32 v74, v43, v43
	v_fmac_f32_e32 v71, v40, v40
	v_fmac_f32_e32 v74, v42, v42
	v_add_f32_e32 v71, v71, v74
	v_fmamk_f32 v11, v133, 0xba800000, v11
	v_fmamk_f32 v9, v133, 0xba800000, v9
	v_add_f32_e32 v70, v71, v70
	v_fmamk_f32 v10, v133, 0xba800000, v10
	v_fmac_f32_e32 v8, 0xba800000, v133
	v_mul_f32_e32 v71, v9, v9
	v_mul_f32_e32 v74, v11, v11
	v_fmac_f32_e32 v71, v8, v8
	v_fmac_f32_e32 v74, v10, v10
	v_mov_b32_e32 v143, v129
	v_add_f32_e32 v71, v71, v74
	v_fmamk_f32 v155, v132, 0xba800000, v103
	v_fmamk_f32 v101, v132, 0xba800000, v101
	v_permlane32_swap_b32_e32 v129, v143
	v_add_f32_e32 v74, v71, v70
	v_fmamk_f32 v154, v132, 0xba800000, v102
	v_fmac_f32_e32 v100, 0xba800000, v132
	v_mul_f32_e32 v70, v101, v101
	v_mul_f32_e32 v71, v155, v155
	v_add_f32_e32 v129, v129, v143
	v_fmac_f32_e32 v70, v100, v100
	v_fmac_f32_e32 v71, v154, v154
	v_fmamk_f32 v143, v132, 0xba800000, v79
	v_fmamk_f32 v77, v132, 0xba800000, v77
	v_add_f32_e32 v70, v70, v71
	v_fmamk_f32 v142, v132, 0xba800000, v78
	v_fmac_f32_e32 v76, 0xba800000, v132
	v_mul_f32_e32 v71, v77, v77
	v_mul_f32_e32 v75, v143, v143
	v_fmac_f32_e32 v71, v76, v76
	v_fmac_f32_e32 v75, v142, v142
	v_add_f32_e32 v71, v71, v75
	v_fmamk_f32 v47, v132, 0xba800000, v47
	v_fmamk_f32 v45, v132, 0xba800000, v45
	v_add_f32_e32 v70, v70, v71
	v_fmamk_f32 v46, v132, 0xba800000, v46
	v_fmac_f32_e32 v44, 0xba800000, v132
	v_mul_f32_e32 v71, v45, v45
	v_mul_f32_e32 v75, v47, v47
	v_fmac_f32_e32 v71, v44, v44
	v_fmac_f32_e32 v75, v46, v46
	v_add_f32_e32 v71, v71, v75
	v_fmamk_f32 v15, v132, 0xba800000, v15
	v_fmamk_f32 v13, v132, 0xba800000, v13
	v_add_f32_e32 v70, v71, v70
	v_fmamk_f32 v14, v132, 0xba800000, v14
	v_fmac_f32_e32 v12, 0xba800000, v132
	v_mul_f32_e32 v71, v13, v13
	v_mul_f32_e32 v75, v15, v15
	v_fmac_f32_e32 v71, v12, v12
	v_fmac_f32_e32 v75, v14, v14
	v_add_f32_e32 v71, v71, v75
	v_fmamk_f32 v157, v131, 0xba800000, v119
	v_fmamk_f32 v117, v131, 0xba800000, v117
	v_add_f32_e32 v75, v71, v70
	v_fmamk_f32 v156, v131, 0xba800000, v118
	v_fmac_f32_e32 v116, 0xba800000, v131
	v_mul_f32_e32 v70, v117, v117
	v_mul_f32_e32 v71, v157, v157
	v_fmac_f32_e32 v70, v116, v116
	v_fmac_f32_e32 v71, v156, v156
	v_fmamk_f32 v145, v131, 0xba800000, v83
	v_fmamk_f32 v81, v131, 0xba800000, v81
	v_add_f32_e32 v70, v70, v71
	v_fmamk_f32 v144, v131, 0xba800000, v82
	v_fmac_f32_e32 v80, 0xba800000, v131
	v_mul_f32_e32 v71, v81, v81
	v_mul_f32_e32 v78, v145, v145
	v_fmac_f32_e32 v71, v80, v80
	v_fmac_f32_e32 v78, v144, v144
	v_add_f32_e32 v71, v71, v78
	v_fmamk_f32 v51, v131, 0xba800000, v51
	v_fmamk_f32 v49, v131, 0xba800000, v49
	v_add_f32_e32 v70, v70, v71
	v_fmamk_f32 v50, v131, 0xba800000, v50
	v_fmac_f32_e32 v48, 0xba800000, v131
	v_mul_f32_e32 v71, v49, v49
	v_mul_f32_e32 v78, v51, v51
	v_fmac_f32_e32 v71, v48, v48
	v_fmac_f32_e32 v78, v50, v50
	v_add_f32_e32 v71, v71, v78
	v_fmamk_f32 v19, v131, 0xba800000, v19
	v_fmamk_f32 v17, v131, 0xba800000, v17
	v_add_f32_e32 v70, v71, v70
	v_fmamk_f32 v18, v131, 0xba800000, v18
	v_fmac_f32_e32 v16, 0xba800000, v131
	v_mul_f32_e32 v71, v17, v17
	v_mul_f32_e32 v78, v19, v19
	v_fmac_f32_e32 v71, v16, v16
	v_fmac_f32_e32 v78, v18, v18
	v_add_f32_e32 v71, v71, v78
	v_fmamk_f32 v159, v130, 0xba800000, v115
	v_fmamk_f32 v113, v130, 0xba800000, v113
	v_add_f32_e32 v79, v71, v70
	v_fmamk_f32 v158, v130, 0xba800000, v114
	v_fmac_f32_e32 v112, 0xba800000, v130
	v_mul_f32_e32 v70, v113, v113
	v_mul_f32_e32 v71, v159, v159
	v_fmac_f32_e32 v70, v112, v112
	v_fmac_f32_e32 v71, v158, v158
	v_fmamk_f32 v147, v130, 0xba800000, v87
	v_fmamk_f32 v85, v130, 0xba800000, v85
	v_add_f32_e32 v70, v70, v71
	v_fmamk_f32 v146, v130, 0xba800000, v86
	v_fmac_f32_e32 v84, 0xba800000, v130
	v_mul_f32_e32 v71, v85, v85
	v_mul_f32_e32 v78, v147, v147
	v_fmac_f32_e32 v71, v84, v84
	v_fmac_f32_e32 v78, v146, v146
	v_add_f32_e32 v71, v71, v78
	v_fmamk_f32 v55, v130, 0xba800000, v55
	v_fmamk_f32 v53, v130, 0xba800000, v53
	v_add_f32_e32 v70, v70, v71
	v_fmamk_f32 v54, v130, 0xba800000, v54
	v_fmac_f32_e32 v52, 0xba800000, v130
	v_mul_f32_e32 v71, v53, v53
	v_mul_f32_e32 v78, v55, v55
	v_fmac_f32_e32 v71, v52, v52
	v_fmac_f32_e32 v78, v54, v54
	v_add_f32_e32 v71, v71, v78
	v_fmamk_f32 v23, v130, 0xba800000, v23
	v_fmamk_f32 v21, v130, 0xba800000, v21
	v_add_f32_e32 v70, v71, v70
	v_fmamk_f32 v22, v130, 0xba800000, v22
	v_fmac_f32_e32 v20, 0xba800000, v130
	v_mul_f32_e32 v71, v21, v21
	v_mul_f32_e32 v78, v23, v23
	v_fmac_f32_e32 v71, v20, v20
	v_fmac_f32_e32 v78, v22, v22
	v_add_f32_e32 v71, v71, v78
	v_fmamk_f32 v161, v129, 0xba800000, v127
	v_fmamk_f32 v125, v129, 0xba800000, v125
	v_add_f32_e32 v83, v71, v70
	v_fmamk_f32 v160, v129, 0xba800000, v126
	v_fmac_f32_e32 v124, 0xba800000, v129
	v_mul_f32_e32 v70, v125, v125
	v_mul_f32_e32 v71, v161, v161
	v_fmac_f32_e32 v70, v124, v124
	v_fmac_f32_e32 v71, v160, v160
	v_fmamk_f32 v149, v129, 0xba800000, v91
	v_fmamk_f32 v89, v129, 0xba800000, v89
	v_add_f32_e32 v70, v70, v71
	v_fmamk_f32 v148, v129, 0xba800000, v90
	v_fmac_f32_e32 v88, 0xba800000, v129
	v_mul_f32_e32 v71, v89, v89
	v_mul_f32_e32 v78, v149, v149
	v_fmac_f32_e32 v71, v88, v88
	v_fmac_f32_e32 v78, v148, v148
	v_add_f32_e32 v71, v71, v78
	v_fmamk_f32 v59, v129, 0xba800000, v59
	v_fmamk_f32 v57, v129, 0xba800000, v57
	v_add_f32_e32 v70, v70, v71
	v_fmamk_f32 v58, v129, 0xba800000, v58
	v_fmac_f32_e32 v56, 0xba800000, v129
	v_mul_f32_e32 v71, v57, v57
	v_mul_f32_e32 v78, v59, v59
	v_fmac_f32_e32 v71, v56, v56
	v_fmac_f32_e32 v78, v58, v58
	v_add_f32_e32 v71, v71, v78
	v_fmamk_f32 v27, v129, 0xba800000, v27
	v_fmamk_f32 v25, v129, 0xba800000, v25
	v_add_f32_e32 v70, v71, v70
	v_fmamk_f32 v26, v129, 0xba800000, v26
	v_fmac_f32_e32 v24, 0xba800000, v129
	v_mul_f32_e32 v71, v25, v25
	v_mul_f32_e32 v78, v27, v27
	v_fmac_f32_e32 v71, v24, v24
	v_fmac_f32_e32 v78, v26, v26
	v_add_f32_e32 v71, v71, v78
	v_fmamk_f32 v163, v128, 0xba800000, v123
	v_fmamk_f32 v121, v128, 0xba800000, v121
	v_add_f32_e32 v87, v71, v70
	v_fmamk_f32 v162, v128, 0xba800000, v122
	v_fmac_f32_e32 v120, 0xba800000, v128
	v_mul_f32_e32 v70, v121, v121
	v_mul_f32_e32 v71, v163, v163
	v_fmac_f32_e32 v70, v120, v120
	v_fmac_f32_e32 v71, v162, v162
	v_fmamk_f32 v123, v128, 0xba800000, v95
	v_fmamk_f32 v93, v128, 0xba800000, v93
	v_add_f32_e32 v70, v70, v71
	v_fmamk_f32 v122, v128, 0xba800000, v94
	v_fmac_f32_e32 v92, 0xba800000, v128
	v_mul_f32_e32 v71, v93, v93
	v_mul_f32_e32 v78, v123, v123
	v_fmac_f32_e32 v71, v92, v92
	v_fmac_f32_e32 v78, v122, v122
	v_add_f32_e32 v71, v71, v78
	v_add_f32_e32 v78, v70, v71
	v_fmamk_f32 v70, v128, 0xba800000, v62
	ds_swizzle_b32 v62, v166 offset:swizzle(SWAP,1)
	v_fmamk_f32 v71, v128, 0xba800000, v63
	v_fmamk_f32 v61, v128, 0xba800000, v61
	v_fmac_f32_e32 v60, 0xba800000, v128
	v_mul_f32_e32 v63, v61, v61
	s_waitcnt lgkmcnt(0)
	v_add_f32_e32 v62, v166, v62
	ds_swizzle_b32 v86, v62 offset:swizzle(SWAP,2)
	v_mul_f32_e32 v82, v71, v71
	v_fmac_f32_e32 v63, v60, v60
	v_fmac_f32_e32 v82, v70, v70
	v_add_f32_e32 v63, v63, v82
	s_waitcnt lgkmcnt(0)
	v_add_f32_e32 v62, v62, v86
	v_add_f32_e32 v63, v63, v78
	ds_swizzle_b32 v78, v62 offset:swizzle(SWAP,4)
	ds_swizzle_b32 v82, v167 offset:swizzle(SWAP,1)
	v_fmamk_f32 v31, v128, 0xba800000, v31
	v_fmamk_f32 v29, v128, 0xba800000, v29
	v_fmamk_f32 v30, v128, 0xba800000, v30
	s_waitcnt lgkmcnt(1)
	v_add_f32_e32 v62, v62, v78
	s_waitcnt lgkmcnt(0)
	v_add_f32_e32 v82, v167, v82
	ds_swizzle_b32 v78, v62 offset:swizzle(SWAP,8)
	ds_swizzle_b32 v90, v82 offset:swizzle(SWAP,2)
	v_fmac_f32_e32 v28, 0xba800000, v128
	v_mul_f32_e32 v86, v29, v29
	v_mul_f32_e32 v91, v31, v31
	s_waitcnt lgkmcnt(1)
	v_add_f32_e32 v62, v62, v78
	s_waitcnt lgkmcnt(0)
	v_add_f32_e32 v82, v82, v90
	ds_swizzle_b32 v78, v62 offset:swizzle(SWAP,16)
	ds_swizzle_b32 v90, v82 offset:swizzle(SWAP,4)
	v_fmac_f32_e32 v86, v28, v28
	v_fmac_f32_e32 v91, v30, v30
	v_add_f32_e32 v86, v86, v91
	s_waitcnt lgkmcnt(1)
	v_add_f32_e32 v62, v62, v78
	s_waitcnt lgkmcnt(0)
	v_add_f32_e32 v78, v82, v90
	ds_swizzle_b32 v90, v74 offset:swizzle(SWAP,1)
	ds_swizzle_b32 v82, v78 offset:swizzle(SWAP,8)
	v_add_f32_e32 v63, v86, v63
	v_mov_b32_e32 v86, v62
	s_nop 1
	v_permlane32_swap_b32_e32 v62, v86
	s_waitcnt lgkmcnt(1)
	v_add_f32_e32 v74, v74, v90
	s_waitcnt lgkmcnt(0)
	v_add_f32_e32 v78, v78, v82
	ds_swizzle_b32 v90, v74 offset:swizzle(SWAP,2)
	v_add_f32_e32 v62, v62, v86
	ds_swizzle_b32 v86, v75 offset:swizzle(SWAP,1)
	ds_swizzle_b32 v82, v78 offset:swizzle(SWAP,16)
	ds_swizzle_b32 v91, v83 offset:swizzle(SWAP,1)
	s_waitcnt lgkmcnt(3)
	v_add_f32_e32 v74, v74, v90
	ds_swizzle_b32 v90, v79 offset:swizzle(SWAP,1)
	s_waitcnt lgkmcnt(3)
	v_add_f32_e32 v75, v75, v86
	s_waitcnt lgkmcnt(2)
	v_add_f32_e32 v78, v78, v82
	ds_swizzle_b32 v82, v74 offset:swizzle(SWAP,4)
	ds_swizzle_b32 v86, v75 offset:swizzle(SWAP,2)
	s_waitcnt lgkmcnt(2)
	v_add_f32_e32 v79, v79, v90
	ds_swizzle_b32 v90, v79 offset:swizzle(SWAP,2)
	ds_swizzle_b32 v103, v87 offset:swizzle(SWAP,1)
	s_waitcnt lgkmcnt(3)
	v_add_f32_e32 v74, v74, v82
	s_waitcnt lgkmcnt(2)
	v_add_f32_e32 v75, v75, v86
	ds_swizzle_b32 v82, v74 offset:swizzle(SWAP,8)
	ds_swizzle_b32 v86, v75 offset:swizzle(SWAP,4)
	s_waitcnt lgkmcnt(3)
	v_add_f32_e32 v79, v79, v90
	ds_swizzle_b32 v90, v79 offset:swizzle(SWAP,4)
	v_fmamk_f32 v62, v62, 0x3a800000, v243
	s_waitcnt lgkmcnt(2)
	v_add_f32_e32 v74, v74, v82
	s_waitcnt lgkmcnt(1)
	v_add_f32_e32 v75, v75, v86
	ds_swizzle_b32 v82, v74 offset:swizzle(SWAP,16)
	ds_swizzle_b32 v86, v75 offset:swizzle(SWAP,8)
	s_waitcnt lgkmcnt(2)
	v_add_f32_e32 v79, v79, v90
	ds_swizzle_b32 v90, v79 offset:swizzle(SWAP,8)
	v_cmp_gt_f32_e32 vcc, s84, v62
	s_waitcnt lgkmcnt(2)
	v_add_f32_e32 v82, v74, v82
	s_waitcnt lgkmcnt(1)
	v_add_f32_e32 v74, v75, v86
	ds_swizzle_b32 v75, v74 offset:swizzle(SWAP,16)
	v_mov_b32_e32 v102, v78
	v_mov_b32_e32 v95, v82
	s_nop 0
	v_permlane32_swap_b32_e32 v78, v102
	s_waitcnt lgkmcnt(0)
	v_add_f32_e32 v86, v74, v75
	v_add_f32_e32 v74, v79, v90
	v_add_f32_e32 v79, v83, v91
	ds_swizzle_b32 v75, v74 offset:swizzle(SWAP,16)
	ds_swizzle_b32 v83, v79 offset:swizzle(SWAP,2)
	v_mov_b32_e32 v94, v86
	v_permlane32_swap_b32_e32 v82, v95
	s_waitcnt lgkmcnt(1)
	v_add_f32_e32 v90, v74, v75
	s_waitcnt lgkmcnt(0)
	v_add_f32_e32 v74, v79, v83
	v_add_f32_e32 v79, v87, v103
	ds_swizzle_b32 v87, v63 offset:swizzle(SWAP,1)
	ds_swizzle_b32 v75, v74 offset:swizzle(SWAP,4)
	ds_swizzle_b32 v83, v79 offset:swizzle(SWAP,2)
	v_mov_b32_e32 v91, v90
	v_permlane32_swap_b32_e32 v86, v94
	s_waitcnt lgkmcnt(2)
	v_add_f32_e32 v63, v63, v87
	s_waitcnt lgkmcnt(1)
	v_add_f32_e32 v74, v74, v75
	s_waitcnt lgkmcnt(0)
	v_add_f32_e32 v79, v79, v83
	ds_swizzle_b32 v87, v63 offset:swizzle(SWAP,2)
	ds_swizzle_b32 v75, v74 offset:swizzle(SWAP,8)
	ds_swizzle_b32 v83, v79 offset:swizzle(SWAP,4)
	v_permlane32_swap_b32_e32 v90, v91
	s_waitcnt lgkmcnt(2)
	v_add_f32_e32 v63, v63, v87
	s_waitcnt lgkmcnt(1)
	v_add_f32_e32 v74, v74, v75
	s_waitcnt lgkmcnt(0)
	v_add_f32_e32 v79, v79, v83
	ds_swizzle_b32 v114, v63 offset:swizzle(SWAP,4)
	ds_swizzle_b32 v75, v74 offset:swizzle(SWAP,16)
	ds_swizzle_b32 v103, v79 offset:swizzle(SWAP,8)
	s_waitcnt lgkmcnt(2)
	v_add_f32_e32 v63, v63, v114
	s_waitcnt lgkmcnt(1)
	v_add_f32_e32 v83, v74, v75
	s_waitcnt lgkmcnt(0)
	v_add_f32_e32 v74, v79, v103
	ds_swizzle_b32 v103, v63 offset:swizzle(SWAP,8)
	ds_swizzle_b32 v75, v74 offset:swizzle(SWAP,16)
	v_mov_b32_e32 v87, v83
	s_nop 1
	v_permlane32_swap_b32_e32 v83, v87
	s_waitcnt lgkmcnt(1)
	v_add_f32_e32 v63, v63, v103
	v_mul_f32_e32 v103, 0x4f800000, v62
	s_waitcnt lgkmcnt(0)
	v_add_f32_e32 v75, v74, v75
	ds_swizzle_b32 v74, v63 offset:swizzle(SWAP,16)
	v_cndmask_b32_e32 v103, v62, v103, vcc
	v_sqrt_f32_e32 v114, v103
	v_mov_b32_e32 v79, v75
	s_nop 1
	v_permlane32_swap_b32_e32 v75, v79
	s_waitcnt lgkmcnt(0)
	v_add_f32_e32 v62, v63, v74
	v_add_u32_e32 v63, -1, v114
	v_fma_f32 v74, -v63, v114, v103
	v_cmp_ge_f32_e64 s[6:7], 0, v74
	v_add_u32_e32 v74, 1, v114
	s_nop 0
	v_cndmask_b32_e64 v63, v114, v63, s[6:7]
	v_fma_f32 v114, -v74, v114, v103
	v_cmp_lt_f32_e64 s[6:7], 0, v114
	s_nop 1
	v_cndmask_b32_e64 v63, v63, v74, s[6:7]
	v_mul_f32_e32 v74, 0x37800000, v63
	v_cndmask_b32_e32 v63, v63, v74, vcc
	v_cmp_class_f32_e32 vcc, v103, v248
	s_nop 1
	v_cndmask_b32_e32 v74, v63, v103, vcc
	v_div_scale_f32 v103, s[6:7], v74, v74, 1.0
	v_rcp_f32_e32 v114, v103
	v_mov_b32_e32 v63, v62
	s_nop 1
	v_permlane32_swap_b32_e32 v62, v63
	v_fma_f32 v115, -v103, v114, 1.0
	v_fmac_f32_e32 v114, v115, v114
	v_div_scale_f32 v115, vcc, 1.0, v74, 1.0
	v_mul_f32_e32 v118, v115, v114
	v_fma_f32 v119, -v103, v118, v115
	v_fmac_f32_e32 v118, v119, v114
	v_fma_f32 v103, -v103, v118, v115
	v_div_fmas_f32 v103, v103, v114, v118
	v_div_fixup_f32 v74, v103, v74, 1.0
	s_and_saveexec_b64 s[6:7], s[4:5]
	s_cbranch_execz .LBB0_1225
	v_mov_b32_e32 v103, s13
	v_add_co_u32_e32 v118, vcc, 0x1fa00000, v103
	v_mov_b32_e32 v103, s11
	v_mul_f32_e32 v114, 0x3a800000, v165
	v_addc_co_u32_e32 v119, vcc, 0, v103, vcc
	v_mov_b32_e32 v115, v74
	global_store_dwordx2 v[118:119], v[114:115], off

.LBB0_1559:
	v_add_co_u32_e32 v0, vcc, 0xffff8400, v140
	s_add_u32 s13, s0, s14
	s_nop 0
	v_addc_co_u32_e32 v1, vcc, -1, v141, vcc
	v_add_co_u32_e32 v2, vcc, 0xffff8800, v140
	s_addc_u32 s11, s1, s15
	s_nop 0
	v_addc_co_u32_e32 v3, vcc, -1, v141, vcc
	global_load_dwordx4 v[104:107], v[0:1], off nt
	s_nop 1
	global_load_dwordx4 v[64:67], v[2:3], off nt
	v_add_co_u32_e32 v0, vcc, 0xffff8c00, v140
	s_nop 1
	s_nop 1
	v_addc_co_u32_e32 v1, vcc, -1, v141, vcc
	v_add_co_u32_e32 v2, vcc, 0xffff9000, v140
	s_nop 1
	s_nop 0
	v_addc_co_u32_e32 v3, vcc, -1, v141, vcc
	v_add_co_u32_e32 v4, vcc, 0xffff9400, v140
	global_load_dwordx4 v[32:35], v[0:1], off nt
	s_nop 0
	global_load_dwordx4 v[0:3], v[2:3], off nt
	v_addc_co_u32_e32 v5, vcc, -1, v141, vcc
	v_add_co_u32_e32 v6, vcc, 0xffff9800, v140
	s_nop 1
	s_nop 0
	v_addc_co_u32_e32 v7, vcc, -1, v141, vcc
	global_load_dwordx4 v[96:99], v[4:5], off nt
	global_load_dwordx4 v[68:71], v[6:7], off nt
	v_add_co_u32_e32 v4, vcc, 0xffff9c00, v140
	s_nop 1
	s_nop 1
	v_addc_co_u32_e32 v5, vcc, -1, v141, vcc
	v_add_co_u32_e32 v6, vcc, 0xffffa000, v140
	s_nop 1
	s_nop 0
	v_addc_co_u32_e32 v7, vcc, -1, v141, vcc
	v_add_co_u32_e32 v8, vcc, 0xffffa400, v140
	global_load_dwordx4 v[36:39], v[4:5], off nt
	s_nop 0
	global_load_dwordx4 v[4:7], v[6:7], off nt
	v_addc_co_u32_e32 v9, vcc, -1, v141, vcc
	v_add_co_u32_e32 v10, vcc, 0xffffa800, v140
	s_nop 1
	s_nop 0
	v_addc_co_u32_e32 v11, vcc, -1, v141, vcc
	global_load_dwordx4 v[108:111], v[8:9], off nt
	global_load_dwordx4 v[72:75], v[10:11], off nt
	v_add_co_u32_e32 v8, vcc, 0xffffac00, v140
	s_nop 1
	s_nop 0
	v_addc_co_u32_e32 v9, vcc, -1, v141, vcc
	v_add_co_u32_e32 v10, vcc, 0xffffb000, v140
	s_nop 1
	s_nop 0
	v_addc_co_u32_e32 v11, vcc, -1, v141, vcc
	v_add_co_u32_e32 v12, vcc, 0xffffb400, v140
	global_load_dwordx4 v[40:43], v[8:9], off nt
	s_nop 0
	global_load_dwordx4 v[8:11], v[10:11], off nt
	v_addc_co_u32_e32 v13, vcc, -1, v141, vcc
	v_add_co_u32_e32 v14, vcc, 0xffffb800, v140
	s_nop 1
	s_nop 1
	v_addc_co_u32_e32 v15, vcc, -1, v141, vcc
	global_load_dwordx4 v[100:103], v[12:13], off nt
	global_load_dwordx4 v[76:79], v[14:15], off nt
	v_add_co_u32_e32 v12, vcc, 0xffffbc00, v140
	s_nop 1
	s_nop 0
	v_addc_co_u32_e32 v13, vcc, -1, v141, vcc
	v_add_co_u32_e32 v14, vcc, 0xffffc000, v140
	s_nop 1
	s_nop 0
	v_addc_co_u32_e32 v15, vcc, -1, v141, vcc
	v_add_co_u32_e32 v16, vcc, 0xffffc400, v140
	global_load_dwordx4 v[44:47], v[12:13], off nt
	s_nop 0
	global_load_dwordx4 v[12:15], v[14:15], off nt
	v_addc_co_u32_e32 v17, vcc, -1, v141, vcc
	v_add_co_u32_e32 v18, vcc, 0xffffc800, v140
	s_nop 1
	s_nop 0
	v_addc_co_u32_e32 v19, vcc, -1, v141, vcc
	global_load_dwordx4 v[116:119], v[16:17], off nt
	global_load_dwordx4 v[80:83], v[18:19], off nt
	v_add_co_u32_e32 v16, vcc, 0xffffcc00, v140
	s_nop 1
	s_nop 0
	v_addc_co_u32_e32 v17, vcc, -1, v141, vcc
	v_add_co_u32_e32 v18, vcc, 0xffffd000, v140
	s_nop 1
	s_nop 0
	v_addc_co_u32_e32 v19, vcc, -1, v141, vcc
	v_add_co_u32_e32 v20, vcc, 0xffffd400, v140
	global_load_dwordx4 v[48:51], v[16:17], off nt
	s_nop 0
	global_load_dwordx4 v[16:19], v[18:19], off nt
	v_addc_co_u32_e32 v21, vcc, -1, v141, vcc
	v_add_co_u32_e32 v22, vcc, 0xffffd800, v140
	s_nop 1
	s_nop 0
	v_addc_co_u32_e32 v23, vcc, -1, v141, vcc
	global_load_dwordx4 v[112:115], v[20:21], off nt
	global_load_dwordx4 v[84:87], v[22:23], off nt
	v_add_co_u32_e32 v20, vcc, 0xffffdc00, v140
	s_nop 1
	s_nop 0
	v_addc_co_u32_e32 v21, vcc, -1, v141, vcc
	v_add_co_u32_e32 v22, vcc, 0xffffe000, v140
	s_nop 1
	s_nop 0
	v_addc_co_u32_e32 v23, vcc, -1, v141, vcc
	v_add_co_u32_e32 v24, vcc, 0xffffe400, v140
	global_load_dwordx4 v[52:55], v[20:21], off nt
	s_nop 0
	global_load_dwordx4 v[20:23], v[22:23], off nt
	v_addc_co_u32_e32 v25, vcc, -1, v141, vcc
	v_add_co_u32_e32 v26, vcc, s46, v140
	s_nop 1
	s_nop 0
	v_addc_co_u32_e32 v27, vcc, -1, v141, vcc
	global_load_dwordx4 v[124:127], v[24:25], off nt
	global_load_dwordx4 v[88:91], v[26:27], off nt
	v_add_co_u32_e32 v24, vcc, 0xffffec00, v140
	s_nop 1
	s_nop 0
	v_addc_co_u32_e32 v25, vcc, -1, v141, vcc
	v_add_co_u32_e32 v26, vcc, 0xfffff000, v140
	s_nop 1
	s_nop 0
	v_addc_co_u32_e32 v27, vcc, -1, v141, vcc
	global_load_dwordx4 v[56:59], v[24:25], off nt
	s_nop 0
	global_load_dwordx4 v[24:27], v[26:27], off nt
	v_add_co_u32_e32 v28, vcc, 0xfffff400, v140
	s_nop 1
	s_nop 0
	v_addc_co_u32_e32 v29, vcc, -1, v141, vcc
	v_add_co_u32_e32 v30, vcc, 0xfffff800, v140
	s_nop 1
	s_nop 0
	v_addc_co_u32_e32 v31, vcc, -1, v141, vcc
	global_load_dwordx4 v[120:123], v[28:29], off nt
	global_load_dwordx4 v[92:95], v[30:31], off nt
	v_add_co_u32_e32 v28, vcc, s76, v140
	s_nop 1
	s_nop 0
	v_addc_co_u32_e32 v29, vcc, -1, v141, vcc
	global_load_dwordx4 v[60:63], v[28:29], off nt
	s_nop 0
	global_load_dwordx4 v[28:31], v[140:141], off nt
	s_waitcnt vmcnt(0) lgkmcnt(0)
	v_add_f32_e32 v128, v104, v105
	v_add_f32_e32 v129, v106, v107
	v_add_f32_e32 v128, v128, v129
	v_add_f32_e32 v129, v64, v65
	v_add_f32_e32 v130, v66, v67
	v_add_f32_e32 v128, 0, v128
	v_add_f32_e32 v129, v129, v130
	v_add_f32_e32 v128, v128, v129
	v_add_f32_e32 v129, v32, v33
	v_add_f32_e32 v130, v34, v35
	v_add_f32_e32 v129, v129, v130
	v_add_f32_e32 v128, v128, v129
	v_add_f32_e32 v129, v0, v1
	v_add_f32_e32 v130, v2, v3
	v_add_f32_e32 v129, v129, v130
	v_add_f32_e32 v128, v128, v129
	v_add_f32_e32 v129, v96, v97
	v_add_f32_e32 v130, v98, v99
	v_add_f32_e32 v129, v129, v130
	v_add_f32_e32 v130, v68, v69
	v_add_f32_e32 v131, v70, v71
	v_add_f32_e32 v129, 0, v129
	v_add_f32_e32 v130, v130, v131
	v_add_f32_e32 v129, v129, v130
	s_waitcnt vmcnt(0)
	v_add_f32_e32 v130, v36, v37
	v_add_f32_e32 v131, v38, v39
	v_add_f32_e32 v130, v130, v131
	v_add_f32_e32 v129, v129, v130
	v_add_f32_e32 v130, v4, v5
	v_add_f32_e32 v131, v6, v7
	v_add_f32_e32 v130, v130, v131
	v_add_f32_e32 v129, v129, v130
	v_add_f32_e32 v130, v108, v109
	v_add_f32_e32 v131, v110, v111
	v_add_f32_e32 v130, v130, v131
	v_add_f32_e32 v131, v72, v73
	v_add_f32_e32 v132, v74, v75
	v_add_f32_e32 v130, 0, v130
	v_add_f32_e32 v131, v131, v132
	v_add_f32_e32 v130, v130, v131
	v_add_f32_e32 v131, v40, v41
	v_add_f32_e32 v132, v42, v43
	v_add_f32_e32 v131, v131, v132
	v_add_f32_e32 v130, v130, v131
	v_add_f32_e32 v131, v8, v9
	v_add_f32_e32 v132, v10, v11
	v_add_f32_e32 v131, v131, v132
	v_add_f32_e32 v130, v130, v131
	s_waitcnt lgkmcnt(0)
	v_add_f32_e32 v131, v100, v101
	v_add_f32_e32 v132, v102, v103
	v_add_f32_e32 v131, v131, v132
	v_add_f32_e32 v132, v76, v77
	v_add_f32_e32 v133, v78, v79
	v_add_f32_e32 v131, 0, v131
	v_add_f32_e32 v132, v132, v133
	v_add_f32_e32 v131, v131, v132
	v_add_f32_e32 v132, v44, v45
	v_add_f32_e32 v133, v46, v47
	v_add_f32_e32 v132, v132, v133
	v_add_f32_e32 v131, v131, v132
	v_add_f32_e32 v132, v12, v13
	v_add_f32_e32 v133, v14, v15
	v_add_f32_e32 v132, v132, v133
	v_add_f32_e32 v131, v131, v132
	v_add_f32_e32 v132, v116, v117
	v_add_f32_e32 v133, v118, v119
	v_add_f32_e32 v132, v132, v133
	v_add_f32_e32 v133, v80, v81
	v_add_f32_e32 v142, v82, v83
	v_add_f32_e32 v132, 0, v132
	v_add_f32_e32 v133, v133, v142
	v_add_f32_e32 v132, v132, v133
	v_add_f32_e32 v133, v48, v49
	v_add_f32_e32 v142, v50, v51
	v_add_f32_e32 v133, v133, v142
	v_add_f32_e32 v132, v132, v133
	v_add_f32_e32 v133, v16, v17
	v_add_f32_e32 v142, v18, v19
	v_add_f32_e32 v133, v133, v142
	v_add_f32_e32 v132, v132, v133
	v_add_f32_e32 v133, v112, v113
	v_add_f32_e32 v142, v114, v115
	v_add_f32_e32 v133, v133, v142
	v_add_f32_e32 v142, v84, v85
	v_add_f32_e32 v143, v86, v87
	v_add_f32_e32 v133, 0, v133
	v_add_f32_e32 v142, v142, v143
	v_add_f32_e32 v133, v133, v142
	v_add_f32_e32 v142, v52, v53
	v_add_f32_e32 v143, v54, v55
	v_add_f32_e32 v142, v142, v143
	v_add_f32_e32 v133, v133, v142
	v_add_f32_e32 v142, v20, v21
	v_add_f32_e32 v143, v22, v23
	v_add_f32_e32 v142, v142, v143
	v_add_f32_e32 v142, v133, v142
	v_add_f32_e32 v133, v124, v125
	v_add_f32_e32 v143, v126, v127
	v_add_f32_e32 v133, v133, v143
	v_add_f32_e32 v143, v88, v89
	v_add_f32_e32 v144, v90, v91
	v_add_f32_e32 v133, 0, v133
	v_add_f32_e32 v143, v143, v144
	v_add_f32_e32 v133, v133, v143
	v_add_f32_e32 v143, v56, v57
	v_add_f32_e32 v144, v58, v59
	v_add_f32_e32 v143, v143, v144
	v_add_f32_e32 v133, v133, v143
	v_add_f32_e32 v143, v24, v25
	v_add_f32_e32 v144, v26, v27
	v_add_f32_e32 v143, v143, v144
	v_add_f32_e32 v143, v133, v143
	v_add_f32_e32 v133, v120, v121
	v_add_f32_e32 v144, v122, v123
	v_add_f32_e32 v133, v133, v144
	ds_swizzle_b32 v144, v128 offset:swizzle(SWAP,1)
	v_add_f32_e32 v145, v92, v93
	v_add_f32_e32 v146, v94, v95
	v_add_f32_e32 v133, 0, v133
	v_add_f32_e32 v145, v145, v146
	s_waitcnt lgkmcnt(0)
	v_add_f32_e32 v128, v128, v144
	v_add_f32_e32 v133, v133, v145
	ds_swizzle_b32 v145, v129 offset:swizzle(SWAP,1)
	ds_swizzle_b32 v144, v128 offset:swizzle(SWAP,2)
	v_add_f32_e32 v146, v60, v61
	v_add_f32_e32 v147, v62, v63
	v_add_f32_e32 v146, v146, v147
	s_waitcnt lgkmcnt(1)
	v_add_f32_e32 v129, v129, v145
	s_waitcnt lgkmcnt(0)
	v_add_f32_e32 v128, v128, v144
	ds_swizzle_b32 v145, v129 offset:swizzle(SWAP,2)
	ds_swizzle_b32 v144, v128 offset:swizzle(SWAP,4)
	v_add_f32_e32 v133, v133, v146
	v_add_f32_e32 v146, v28, v29
	v_add_f32_e32 v147, v30, v31
	s_waitcnt lgkmcnt(1)
	v_add_f32_e32 v129, v129, v145
	s_waitcnt lgkmcnt(0)
	v_add_f32_e32 v128, v128, v144
	ds_swizzle_b32 v145, v129 offset:swizzle(SWAP,4)
	ds_swizzle_b32 v144, v128 offset:swizzle(SWAP,8)
	v_add_f32_e32 v146, v146, v147
	v_add_f32_e32 v146, v133, v146
	s_waitcnt lgkmcnt(1)
	v_add_f32_e32 v129, v129, v145
	s_waitcnt lgkmcnt(0)
	v_add_f32_e32 v128, v128, v144
	ds_swizzle_b32 v145, v129 offset:swizzle(SWAP,8)
	ds_swizzle_b32 v144, v128 offset:swizzle(SWAP,16)
	s_waitcnt lgkmcnt(1)
	v_add_f32_e32 v129, v129, v145
	s_waitcnt lgkmcnt(0)
	v_add_f32_e32 v128, v128, v144
	ds_swizzle_b32 v144, v129 offset:swizzle(SWAP,16)
	ds_swizzle_b32 v145, v130 offset:swizzle(SWAP,1)
	v_mov_b32_e32 v133, v128
	s_nop 1
	v_permlane32_swap_b32_e32 v128, v133
	v_add_f32_e32 v165, v128, v133
	s_waitcnt lgkmcnt(1)
	v_add_f32_e32 v128, v129, v144
	ds_swizzle_b32 v144, v131 offset:swizzle(SWAP,1)
	s_waitcnt lgkmcnt(1)
	v_add_f32_e32 v129, v130, v145
	ds_swizzle_b32 v130, v129 offset:swizzle(SWAP,2)
	v_mov_b32_e32 v133, v128
	s_nop 1
	v_permlane32_swap_b32_e32 v128, v133
	s_waitcnt lgkmcnt(1)
	v_add_f32_e32 v131, v131, v144
	ds_swizzle_b32 v144, v131 offset:swizzle(SWAP,2)
	v_add_f32_e32 v164, v128, v133
	ds_swizzle_b32 v128, v132 offset:swizzle(SWAP,1)
	s_waitcnt lgkmcnt(2)
	v_add_f32_e32 v129, v129, v130
	ds_swizzle_b32 v130, v129 offset:swizzle(SWAP,4)
	s_waitcnt lgkmcnt(2)
	v_add_f32_e32 v131, v131, v144
	ds_swizzle_b32 v133, v131 offset:swizzle(SWAP,4)
	s_waitcnt lgkmcnt(2)
	v_add_f32_e32 v128, v132, v128
	ds_swizzle_b32 v132, v128 offset:swizzle(SWAP,2)
	s_waitcnt lgkmcnt(2)
	v_add_f32_e32 v129, v129, v130
	ds_swizzle_b32 v130, v129 offset:swizzle(SWAP,8)
	s_waitcnt lgkmcnt(2)
	v_add_f32_e32 v131, v131, v133
	ds_swizzle_b32 v133, v131 offset:swizzle(SWAP,8)
	s_waitcnt lgkmcnt(2)
	v_add_f32_e32 v128, v128, v132
	ds_swizzle_b32 v132, v128 offset:swizzle(SWAP,4)
	s_waitcnt lgkmcnt(2)
	v_add_f32_e32 v129, v129, v130
	ds_swizzle_b32 v130, v129 offset:swizzle(SWAP,16)
	s_waitcnt lgkmcnt(2)
	v_add_f32_e32 v131, v131, v133
	ds_swizzle_b32 v144, v131 offset:swizzle(SWAP,16)
	s_waitcnt lgkmcnt(2)
	v_add_f32_e32 v128, v128, v132
	ds_swizzle_b32 v132, v128 offset:swizzle(SWAP,8)
	s_waitcnt lgkmcnt(2)
	v_add_f32_e32 v129, v129, v130
	v_mov_b32_e32 v130, v129
	s_nop 1
	v_permlane32_swap_b32_e32 v129, v130
	v_add_f32_e32 v133, v129, v130
	s_waitcnt lgkmcnt(1)
	v_add_f32_e32 v129, v131, v144
	ds_swizzle_b32 v144, v142 offset:swizzle(SWAP,1)
	s_waitcnt lgkmcnt(1)
	v_add_f32_e32 v128, v128, v132
	ds_swizzle_b32 v131, v128 offset:swizzle(SWAP,16)
	v_mov_b32_e32 v130, v129
	s_nop 1
	v_permlane32_swap_b32_e32 v129, v130
	v_add_f32_e32 v132, v129, v130
	s_waitcnt lgkmcnt(1)
	v_add_f32_e32 v129, v142, v144
	ds_swizzle_b32 v142, v143 offset:swizzle(SWAP,1)
	s_waitcnt lgkmcnt(1)
	v_add_f32_e32 v128, v128, v131
	ds_swizzle_b32 v130, v129 offset:swizzle(SWAP,2)
	v_mov_b32_e32 v131, v128
	s_nop 1
	v_permlane32_swap_b32_e32 v128, v131
	s_waitcnt lgkmcnt(1)
	v_add_f32_e32 v142, v143, v142
	v_add_f32_e32 v131, v128, v131
	ds_swizzle_b32 v128, v146 offset:swizzle(SWAP,1)
	ds_swizzle_b32 v143, v142 offset:swizzle(SWAP,2)
	s_waitcnt lgkmcnt(2)
	v_add_f32_e32 v129, v129, v130
	ds_swizzle_b32 v130, v129 offset:swizzle(SWAP,4)
	v_fmamk_f32 v151, v165, 0xba800000, v107
	s_waitcnt lgkmcnt(2)
	v_add_f32_e32 v128, v146, v128
	s_waitcnt lgkmcnt(1)
	v_add_f32_e32 v142, v142, v143
	ds_swizzle_b32 v144, v128 offset:swizzle(SWAP,2)
	ds_swizzle_b32 v143, v142 offset:swizzle(SWAP,4)
	s_waitcnt lgkmcnt(2)
	v_add_f32_e32 v129, v129, v130
	ds_swizzle_b32 v130, v129 offset:swizzle(SWAP,8)
	v_fmamk_f32 v105, v165, 0xba800000, v105
	s_waitcnt lgkmcnt(2)
	v_add_f32_e32 v128, v128, v144
	s_waitcnt lgkmcnt(1)
	v_add_f32_e32 v142, v142, v143
	ds_swizzle_b32 v144, v128 offset:swizzle(SWAP,4)
	ds_swizzle_b32 v143, v142 offset:swizzle(SWAP,8)
	s_waitcnt lgkmcnt(2)
	v_add_f32_e32 v129, v129, v130
	ds_swizzle_b32 v130, v129 offset:swizzle(SWAP,16)
	v_fmamk_f32 v150, v165, 0xba800000, v106
	s_waitcnt lgkmcnt(2)
	v_add_f32_e32 v128, v128, v144
	s_waitcnt lgkmcnt(1)
	v_add_f32_e32 v142, v142, v143
	ds_swizzle_b32 v144, v128 offset:swizzle(SWAP,8)
	ds_swizzle_b32 v143, v142 offset:swizzle(SWAP,16)
	s_waitcnt lgkmcnt(2)
	v_add_f32_e32 v129, v129, v130
	v_mov_b32_e32 v130, v129
	s_nop 1
	v_permlane32_swap_b32_e32 v129, v130
	s_waitcnt lgkmcnt(1)
	v_add_f32_e32 v128, v128, v144
	v_add_f32_e32 v130, v129, v130
	s_waitcnt lgkmcnt(0)
	v_add_f32_e32 v129, v142, v143
	ds_swizzle_b32 v142, v128 offset:swizzle(SWAP,16)
	v_fmac_f32_e32 v104, 0xba800000, v165
	v_mul_f32_e32 v106, v105, v105
	v_mul_f32_e32 v107, v151, v151
	v_fmac_f32_e32 v106, v104, v104
	s_waitcnt lgkmcnt(0)
	v_add_f32_e32 v128, v128, v142
	v_mov_b32_e32 v142, v128
	s_nop 1
	v_permlane32_swap_b32_e32 v128, v142
	v_fmac_f32_e32 v107, v150, v150
	v_fmamk_f32 v67, v165, 0xba800000, v67
	v_fmamk_f32 v65, v165, 0xba800000, v65
	v_add_f32_e32 v128, v128, v142
	v_add_f32_e32 v106, v106, v107
	v_fmamk_f32 v66, v165, 0xba800000, v66
	v_fmac_f32_e32 v64, 0xba800000, v165
	v_mul_f32_e32 v107, v65, v65
	v_mul_f32_e32 v142, v67, v67
	v_fmac_f32_e32 v107, v64, v64
	v_fmac_f32_e32 v142, v66, v66
	v_add_f32_e32 v107, v107, v142
	v_fmamk_f32 v35, v165, 0xba800000, v35
	v_fmamk_f32 v33, v165, 0xba800000, v33
	v_add_f32_e32 v106, v106, v107
	v_fmamk_f32 v34, v165, 0xba800000, v34
	v_fmac_f32_e32 v32, 0xba800000, v165
	v_mul_f32_e32 v107, v33, v33
	v_mul_f32_e32 v142, v35, v35
	v_fmac_f32_e32 v107, v32, v32
	v_fmac_f32_e32 v142, v34, v34
	v_add_f32_e32 v107, v107, v142
	v_fmamk_f32 v3, v165, 0xba800000, v3
	v_fmamk_f32 v1, v165, 0xba800000, v1
	v_add_f32_e32 v106, v107, v106
	v_fmamk_f32 v2, v165, 0xba800000, v2
	v_fmac_f32_e32 v0, 0xba800000, v165
	v_mul_f32_e32 v107, v1, v1
	v_mul_f32_e32 v142, v3, v3
	v_fmac_f32_e32 v107, v0, v0
	v_fmac_f32_e32 v142, v2, v2
	v_add_f32_e32 v107, v107, v142
	v_fmamk_f32 v99, v164, 0xba800000, v99
	v_fmamk_f32 v97, v164, 0xba800000, v97
	v_add_f32_e32 v166, v107, v106
	v_fmamk_f32 v98, v164, 0xba800000, v98
	v_fmac_f32_e32 v96, 0xba800000, v164
	v_mul_f32_e32 v106, v97, v97
	v_mul_f32_e32 v107, v99, v99
	v_fmac_f32_e32 v106, v96, v96
	v_fmac_f32_e32 v107, v98, v98
	v_add_f32_e32 v142, v106, v107
	v_fmamk_f32 v107, v164, 0xba800000, v71
	v_fmamk_f32 v69, v164, 0xba800000, v69
	v_fmamk_f32 v106, v164, 0xba800000, v70
	v_fmac_f32_e32 v68, 0xba800000, v164
	v_mul_f32_e32 v70, v69, v69
	v_mul_f32_e32 v71, v107, v107
	v_fmac_f32_e32 v70, v68, v68
	v_fmac_f32_e32 v71, v106, v106
	v_add_f32_e32 v70, v70, v71
	v_fmamk_f32 v39, v164, 0xba800000, v39
	v_fmamk_f32 v37, v164, 0xba800000, v37
	v_add_f32_e32 v70, v142, v70
	v_fmamk_f32 v38, v164, 0xba800000, v38
	v_fmac_f32_e32 v36, 0xba800000, v164
	v_mul_f32_e32 v71, v37, v37
	v_mul_f32_e32 v142, v39, v39
	v_fmac_f32_e32 v71, v36, v36
	v_fmac_f32_e32 v142, v38, v38
	v_add_f32_e32 v71, v71, v142
	v_fmamk_f32 v7, v164, 0xba800000, v7
	v_fmamk_f32 v5, v164, 0xba800000, v5
	v_add_f32_e32 v70, v71, v70
	v_fmamk_f32 v6, v164, 0xba800000, v6
	v_fmac_f32_e32 v4, 0xba800000, v164
	v_mul_f32_e32 v71, v5, v5
	v_mul_f32_e32 v142, v7, v7
	v_fmac_f32_e32 v71, v4, v4
	v_fmac_f32_e32 v142, v6, v6
	v_add_f32_e32 v71, v71, v142
	v_fmamk_f32 v153, v133, 0xba800000, v111
	v_fmamk_f32 v109, v133, 0xba800000, v109
	v_add_f32_e32 v167, v71, v70
	v_fmamk_f32 v152, v133, 0xba800000, v110
	v_fmac_f32_e32 v108, 0xba800000, v133
	v_mul_f32_e32 v70, v109, v109
	v_mul_f32_e32 v71, v153, v153
	v_fmac_f32_e32 v70, v108, v108
	v_fmac_f32_e32 v71, v152, v152
	v_fmamk_f32 v111, v133, 0xba800000, v75
	v_fmamk_f32 v73, v133, 0xba800000, v73
	v_add_f32_e32 v70, v70, v71
	v_fmamk_f32 v110, v133, 0xba800000, v74
	v_fmac_f32_e32 v72, 0xba800000, v133
	v_mul_f32_e32 v71, v73, v73
	v_mul_f32_e32 v74, v111, v111
	v_fmac_f32_e32 v71, v72, v72
	v_fmac_f32_e32 v74, v110, v110
	v_add_f32_e32 v71, v71, v74
	v_fmamk_f32 v43, v133, 0xba800000, v43
	v_fmamk_f32 v41, v133, 0xba800000, v41
	v_add_f32_e32 v70, v70, v71
	v_fmamk_f32 v42, v133, 0xba800000, v42
	v_fmac_f32_e32 v40, 0xba800000, v133
	v_mul_f32_e32 v71, v41, v41
	v_mul_f32_e32 v74, v43, v43
	v_fmac_f32_e32 v71, v40, v40
	v_fmac_f32_e32 v74, v42, v42
	v_add_f32_e32 v71, v71, v74
	v_fmamk_f32 v11, v133, 0xba800000, v11
	v_fmamk_f32 v9, v133, 0xba800000, v9
	v_add_f32_e32 v70, v71, v70
	v_fmamk_f32 v10, v133, 0xba800000, v10
	v_fmac_f32_e32 v8, 0xba800000, v133
	v_mul_f32_e32 v71, v9, v9
	v_mul_f32_e32 v74, v11, v11
	v_fmac_f32_e32 v71, v8, v8
	v_fmac_f32_e32 v74, v10, v10
	v_mov_b32_e32 v143, v129
	v_add_f32_e32 v71, v71, v74
	v_fmamk_f32 v155, v132, 0xba800000, v103
	v_fmamk_f32 v101, v132, 0xba800000, v101
	v_permlane32_swap_b32_e32 v129, v143
	v_add_f32_e32 v74, v71, v70
	v_fmamk_f32 v154, v132, 0xba800000, v102
	v_fmac_f32_e32 v100, 0xba800000, v132
	v_mul_f32_e32 v70, v101, v101
	v_mul_f32_e32 v71, v155, v155
	v_add_f32_e32 v129, v129, v143
	v_fmac_f32_e32 v70, v100, v100
	v_fmac_f32_e32 v71, v154, v154
	v_fmamk_f32 v143, v132, 0xba800000, v79
	v_fmamk_f32 v77, v132, 0xba800000, v77
	v_add_f32_e32 v70, v70, v71
	v_fmamk_f32 v142, v132, 0xba800000, v78
	v_fmac_f32_e32 v76, 0xba800000, v132
	v_mul_f32_e32 v71, v77, v77
	v_mul_f32_e32 v75, v143, v143
	v_fmac_f32_e32 v71, v76, v76
	v_fmac_f32_e32 v75, v142, v142
	v_add_f32_e32 v71, v71, v75
	v_fmamk_f32 v47, v132, 0xba800000, v47
	v_fmamk_f32 v45, v132, 0xba800000, v45
	v_add_f32_e32 v70, v70, v71
	v_fmamk_f32 v46, v132, 0xba800000, v46
	v_fmac_f32_e32 v44, 0xba800000, v132
	v_mul_f32_e32 v71, v45, v45
	v_mul_f32_e32 v75, v47, v47
	v_fmac_f32_e32 v71, v44, v44
	v_fmac_f32_e32 v75, v46, v46
	v_add_f32_e32 v71, v71, v75
	v_fmamk_f32 v15, v132, 0xba800000, v15
	v_fmamk_f32 v13, v132, 0xba800000, v13
	v_add_f32_e32 v70, v71, v70
	v_fmamk_f32 v14, v132, 0xba800000, v14
	v_fmac_f32_e32 v12, 0xba800000, v132
	v_mul_f32_e32 v71, v13, v13
	v_mul_f32_e32 v75, v15, v15
	v_fmac_f32_e32 v71, v12, v12
	v_fmac_f32_e32 v75, v14, v14
	v_add_f32_e32 v71, v71, v75
	v_fmamk_f32 v157, v131, 0xba800000, v119
	v_fmamk_f32 v117, v131, 0xba800000, v117
	v_add_f32_e32 v75, v71, v70
	v_fmamk_f32 v156, v131, 0xba800000, v118
	v_fmac_f32_e32 v116, 0xba800000, v131
	v_mul_f32_e32 v70, v117, v117
	v_mul_f32_e32 v71, v157, v157
	v_fmac_f32_e32 v70, v116, v116
	v_fmac_f32_e32 v71, v156, v156
	v_fmamk_f32 v145, v131, 0xba800000, v83
	v_fmamk_f32 v81, v131, 0xba800000, v81
	v_add_f32_e32 v70, v70, v71
	v_fmamk_f32 v144, v131, 0xba800000, v82
	v_fmac_f32_e32 v80, 0xba800000, v131
	v_mul_f32_e32 v71, v81, v81
	v_mul_f32_e32 v78, v145, v145
	v_fmac_f32_e32 v71, v80, v80
	v_fmac_f32_e32 v78, v144, v144
	v_add_f32_e32 v71, v71, v78
	v_fmamk_f32 v51, v131, 0xba800000, v51
	v_fmamk_f32 v49, v131, 0xba800000, v49
	v_add_f32_e32 v70, v70, v71
	v_fmamk_f32 v50, v131, 0xba800000, v50
	v_fmac_f32_e32 v48, 0xba800000, v131
	v_mul_f32_e32 v71, v49, v49
	v_mul_f32_e32 v78, v51, v51
	v_fmac_f32_e32 v71, v48, v48
	v_fmac_f32_e32 v78, v50, v50
	v_add_f32_e32 v71, v71, v78
	v_fmamk_f32 v19, v131, 0xba800000, v19
	v_fmamk_f32 v17, v131, 0xba800000, v17
	v_add_f32_e32 v70, v71, v70
	v_fmamk_f32 v18, v131, 0xba800000, v18
	v_fmac_f32_e32 v16, 0xba800000, v131
	v_mul_f32_e32 v71, v17, v17
	v_mul_f32_e32 v78, v19, v19
	v_fmac_f32_e32 v71, v16, v16
	v_fmac_f32_e32 v78, v18, v18
	v_add_f32_e32 v71, v71, v78
	v_fmamk_f32 v159, v130, 0xba800000, v115
	v_fmamk_f32 v113, v130, 0xba800000, v113
	v_add_f32_e32 v79, v71, v70
	v_fmamk_f32 v158, v130, 0xba800000, v114
	v_fmac_f32_e32 v112, 0xba800000, v130
	v_mul_f32_e32 v70, v113, v113
	v_mul_f32_e32 v71, v159, v159
	v_fmac_f32_e32 v70, v112, v112
	v_fmac_f32_e32 v71, v158, v158
	v_fmamk_f32 v147, v130, 0xba800000, v87
	v_fmamk_f32 v85, v130, 0xba800000, v85
	v_add_f32_e32 v70, v70, v71
	v_fmamk_f32 v146, v130, 0xba800000, v86
	v_fmac_f32_e32 v84, 0xba800000, v130
	v_mul_f32_e32 v71, v85, v85
	v_mul_f32_e32 v78, v147, v147
	v_fmac_f32_e32 v71, v84, v84
	v_fmac_f32_e32 v78, v146, v146
	v_add_f32_e32 v71, v71, v78
	v_fmamk_f32 v55, v130, 0xba800000, v55
	v_fmamk_f32 v53, v130, 0xba800000, v53
	v_add_f32_e32 v70, v70, v71
	v_fmamk_f32 v54, v130, 0xba800000, v54
	v_fmac_f32_e32 v52, 0xba800000, v130
	v_mul_f32_e32 v71, v53, v53
	v_mul_f32_e32 v78, v55, v55
	v_fmac_f32_e32 v71, v52, v52
	v_fmac_f32_e32 v78, v54, v54
	v_add_f32_e32 v71, v71, v78
	v_fmamk_f32 v23, v130, 0xba800000, v23
	v_fmamk_f32 v21, v130, 0xba800000, v21
	v_add_f32_e32 v70, v71, v70
	v_fmamk_f32 v22, v130, 0xba800000, v22
	v_fmac_f32_e32 v20, 0xba800000, v130
	v_mul_f32_e32 v71, v21, v21
	v_mul_f32_e32 v78, v23, v23
	v_fmac_f32_e32 v71, v20, v20
	v_fmac_f32_e32 v78, v22, v22
	v_add_f32_e32 v71, v71, v78
	v_fmamk_f32 v161, v129, 0xba800000, v127
	v_fmamk_f32 v125, v129, 0xba800000, v125
	v_add_f32_e32 v83, v71, v70
	v_fmamk_f32 v160, v129, 0xba800000, v126
	v_fmac_f32_e32 v124, 0xba800000, v129
	v_mul_f32_e32 v70, v125, v125
	v_mul_f32_e32 v71, v161, v161
	v_fmac_f32_e32 v70, v124, v124
	v_fmac_f32_e32 v71, v160, v160
	v_fmamk_f32 v149, v129, 0xba800000, v91
	v_fmamk_f32 v89, v129, 0xba800000, v89
	v_add_f32_e32 v70, v70, v71
	v_fmamk_f32 v148, v129, 0xba800000, v90
	v_fmac_f32_e32 v88, 0xba800000, v129
	v_mul_f32_e32 v71, v89, v89
	v_mul_f32_e32 v78, v149, v149
	v_fmac_f32_e32 v71, v88, v88
	v_fmac_f32_e32 v78, v148, v148
	v_add_f32_e32 v71, v71, v78
	v_fmamk_f32 v59, v129, 0xba800000, v59
	v_fmamk_f32 v57, v129, 0xba800000, v57
	v_add_f32_e32 v70, v70, v71
	v_fmamk_f32 v58, v129, 0xba800000, v58
	v_fmac_f32_e32 v56, 0xba800000, v129
	v_mul_f32_e32 v71, v57, v57
	v_mul_f32_e32 v78, v59, v59
	v_fmac_f32_e32 v71, v56, v56
	v_fmac_f32_e32 v78, v58, v58
	v_add_f32_e32 v71, v71, v78
	v_fmamk_f32 v27, v129, 0xba800000, v27
	v_fmamk_f32 v25, v129, 0xba800000, v25
	v_add_f32_e32 v70, v71, v70
	v_fmamk_f32 v26, v129, 0xba800000, v26
	v_fmac_f32_e32 v24, 0xba800000, v129
	v_mul_f32_e32 v71, v25, v25
	v_mul_f32_e32 v78, v27, v27
	v_fmac_f32_e32 v71, v24, v24
	v_fmac_f32_e32 v78, v26, v26
	v_add_f32_e32 v71, v71, v78
	v_fmamk_f32 v163, v128, 0xba800000, v123
	v_fmamk_f32 v121, v128, 0xba800000, v121
	v_add_f32_e32 v87, v71, v70
	v_fmamk_f32 v162, v128, 0xba800000, v122
	v_fmac_f32_e32 v120, 0xba800000, v128
	v_mul_f32_e32 v70, v121, v121
	v_mul_f32_e32 v71, v163, v163
	v_fmac_f32_e32 v70, v120, v120
	v_fmac_f32_e32 v71, v162, v162
	v_fmamk_f32 v123, v128, 0xba800000, v95
	v_fmamk_f32 v93, v128, 0xba800000, v93
	v_add_f32_e32 v70, v70, v71
	v_fmamk_f32 v122, v128, 0xba800000, v94
	v_fmac_f32_e32 v92, 0xba800000, v128
	v_mul_f32_e32 v71, v93, v93
	v_mul_f32_e32 v78, v123, v123
	v_fmac_f32_e32 v71, v92, v92
	v_fmac_f32_e32 v78, v122, v122
	v_add_f32_e32 v71, v71, v78
	v_add_f32_e32 v78, v70, v71
	v_fmamk_f32 v70, v128, 0xba800000, v62
	ds_swizzle_b32 v62, v166 offset:swizzle(SWAP,1)
	v_fmamk_f32 v71, v128, 0xba800000, v63
	v_fmamk_f32 v61, v128, 0xba800000, v61
	v_fmac_f32_e32 v60, 0xba800000, v128
	v_mul_f32_e32 v63, v61, v61
	s_waitcnt lgkmcnt(0)
	v_add_f32_e32 v62, v166, v62
	ds_swizzle_b32 v86, v62 offset:swizzle(SWAP,2)
	v_mul_f32_e32 v82, v71, v71
	v_fmac_f32_e32 v63, v60, v60
	v_fmac_f32_e32 v82, v70, v70
	v_add_f32_e32 v63, v63, v82
	s_waitcnt lgkmcnt(0)
	v_add_f32_e32 v62, v62, v86
	v_add_f32_e32 v63, v63, v78
	ds_swizzle_b32 v78, v62 offset:swizzle(SWAP,4)
	ds_swizzle_b32 v82, v167 offset:swizzle(SWAP,1)
	v_fmamk_f32 v31, v128, 0xba800000, v31
	v_fmamk_f32 v29, v128, 0xba800000, v29
	v_fmamk_f32 v30, v128, 0xba800000, v30
	s_waitcnt lgkmcnt(1)
	v_add_f32_e32 v62, v62, v78
	s_waitcnt lgkmcnt(0)
	v_add_f32_e32 v82, v167, v82
	ds_swizzle_b32 v78, v62 offset:swizzle(SWAP,8)
	ds_swizzle_b32 v90, v82 offset:swizzle(SWAP,2)
	v_fmac_f32_e32 v28, 0xba800000, v128
	v_mul_f32_e32 v86, v29, v29
	v_mul_f32_e32 v91, v31, v31
	s_waitcnt lgkmcnt(1)
	v_add_f32_e32 v62, v62, v78
	s_waitcnt lgkmcnt(0)
	v_add_f32_e32 v82, v82, v90
	ds_swizzle_b32 v78, v62 offset:swizzle(SWAP,16)
	ds_swizzle_b32 v90, v82 offset:swizzle(SWAP,4)
	v_fmac_f32_e32 v86, v28, v28
	v_fmac_f32_e32 v91, v30, v30
	v_add_f32_e32 v86, v86, v91
	s_waitcnt lgkmcnt(1)
	v_add_f32_e32 v62, v62, v78
	s_waitcnt lgkmcnt(0)
	v_add_f32_e32 v78, v82, v90
	ds_swizzle_b32 v90, v74 offset:swizzle(SWAP,1)
	ds_swizzle_b32 v82, v78 offset:swizzle(SWAP,8)
	v_add_f32_e32 v63, v86, v63
	v_mov_b32_e32 v86, v62
	s_nop 1
	v_permlane32_swap_b32_e32 v62, v86
	s_waitcnt lgkmcnt(1)
	v_add_f32_e32 v74, v74, v90
	s_waitcnt lgkmcnt(0)
	v_add_f32_e32 v78, v78, v82
	ds_swizzle_b32 v90, v74 offset:swizzle(SWAP,2)
	v_add_f32_e32 v62, v62, v86
	ds_swizzle_b32 v86, v75 offset:swizzle(SWAP,1)
	ds_swizzle_b32 v82, v78 offset:swizzle(SWAP,16)
	ds_swizzle_b32 v91, v83 offset:swizzle(SWAP,1)
	s_waitcnt lgkmcnt(3)
	v_add_f32_e32 v74, v74, v90
	ds_swizzle_b32 v90, v79 offset:swizzle(SWAP,1)
	s_waitcnt lgkmcnt(3)
	v_add_f32_e32 v75, v75, v86
	s_waitcnt lgkmcnt(2)
	v_add_f32_e32 v78, v78, v82
	ds_swizzle_b32 v82, v74 offset:swizzle(SWAP,4)
	ds_swizzle_b32 v86, v75 offset:swizzle(SWAP,2)
	s_waitcnt lgkmcnt(2)
	v_add_f32_e32 v79, v79, v90
	ds_swizzle_b32 v90, v79 offset:swizzle(SWAP,2)
	ds_swizzle_b32 v103, v87 offset:swizzle(SWAP,1)
	s_waitcnt lgkmcnt(3)
	v_add_f32_e32 v74, v74, v82
	s_waitcnt lgkmcnt(2)
	v_add_f32_e32 v75, v75, v86
	ds_swizzle_b32 v82, v74 offset:swizzle(SWAP,8)
	ds_swizzle_b32 v86, v75 offset:swizzle(SWAP,4)
	s_waitcnt lgkmcnt(3)
	v_add_f32_e32 v79, v79, v90
	ds_swizzle_b32 v90, v79 offset:swizzle(SWAP,4)
	v_fmamk_f32 v62, v62, 0x3a800000, v243
	s_waitcnt lgkmcnt(2)
	v_add_f32_e32 v74, v74, v82
	s_waitcnt lgkmcnt(1)
	v_add_f32_e32 v75, v75, v86
	ds_swizzle_b32 v82, v74 offset:swizzle(SWAP,16)
	ds_swizzle_b32 v86, v75 offset:swizzle(SWAP,8)
	s_waitcnt lgkmcnt(2)
	v_add_f32_e32 v79, v79, v90
	ds_swizzle_b32 v90, v79 offset:swizzle(SWAP,8)
	v_cmp_gt_f32_e32 vcc, s84, v62
	s_waitcnt lgkmcnt(2)
	v_add_f32_e32 v82, v74, v82
	s_waitcnt lgkmcnt(1)
	v_add_f32_e32 v74, v75, v86
	ds_swizzle_b32 v75, v74 offset:swizzle(SWAP,16)
	v_mov_b32_e32 v102, v78
	v_mov_b32_e32 v95, v82
	s_nop 0
	v_permlane32_swap_b32_e32 v78, v102
	s_waitcnt lgkmcnt(0)
	v_add_f32_e32 v86, v74, v75
	v_add_f32_e32 v74, v79, v90
	v_add_f32_e32 v79, v83, v91
	ds_swizzle_b32 v75, v74 offset:swizzle(SWAP,16)
	ds_swizzle_b32 v83, v79 offset:swizzle(SWAP,2)
	v_mov_b32_e32 v94, v86
	v_permlane32_swap_b32_e32 v82, v95
	s_waitcnt lgkmcnt(1)
	v_add_f32_e32 v90, v74, v75
	s_waitcnt lgkmcnt(0)
	v_add_f32_e32 v74, v79, v83
	v_add_f32_e32 v79, v87, v103
	ds_swizzle_b32 v87, v63 offset:swizzle(SWAP,1)
	ds_swizzle_b32 v75, v74 offset:swizzle(SWAP,4)
	ds_swizzle_b32 v83, v79 offset:swizzle(SWAP,2)
	v_mov_b32_e32 v91, v90
	v_permlane32_swap_b32_e32 v86, v94
	s_waitcnt lgkmcnt(2)
	v_add_f32_e32 v63, v63, v87
	s_waitcnt lgkmcnt(1)
	v_add_f32_e32 v74, v74, v75
	s_waitcnt lgkmcnt(0)
	v_add_f32_e32 v79, v79, v83
	ds_swizzle_b32 v87, v63 offset:swizzle(SWAP,2)
	ds_swizzle_b32 v75, v74 offset:swizzle(SWAP,8)
	ds_swizzle_b32 v83, v79 offset:swizzle(SWAP,4)
	v_permlane32_swap_b32_e32 v90, v91
	s_waitcnt lgkmcnt(2)
	v_add_f32_e32 v63, v63, v87
	s_waitcnt lgkmcnt(1)
	v_add_f32_e32 v74, v74, v75
	s_waitcnt lgkmcnt(0)
	v_add_f32_e32 v79, v79, v83
	ds_swizzle_b32 v114, v63 offset:swizzle(SWAP,4)
	ds_swizzle_b32 v75, v74 offset:swizzle(SWAP,16)
	ds_swizzle_b32 v103, v79 offset:swizzle(SWAP,8)
	s_waitcnt lgkmcnt(2)
	v_add_f32_e32 v63, v63, v114
	s_waitcnt lgkmcnt(1)
	v_add_f32_e32 v83, v74, v75
	s_waitcnt lgkmcnt(0)
	v_add_f32_e32 v74, v79, v103
	ds_swizzle_b32 v103, v63 offset:swizzle(SWAP,8)
	ds_swizzle_b32 v75, v74 offset:swizzle(SWAP,16)
	v_mov_b32_e32 v87, v83
	s_nop 1
	v_permlane32_swap_b32_e32 v83, v87
	s_waitcnt lgkmcnt(1)
	v_add_f32_e32 v63, v63, v103
	v_mul_f32_e32 v103, 0x4f800000, v62
	s_waitcnt lgkmcnt(0)
	v_add_f32_e32 v75, v74, v75
	ds_swizzle_b32 v74, v63 offset:swizzle(SWAP,16)
	v_cndmask_b32_e32 v103, v62, v103, vcc
	v_sqrt_f32_e32 v114, v103
	v_mov_b32_e32 v79, v75
	s_nop 1
	v_permlane32_swap_b32_e32 v75, v79
	s_waitcnt lgkmcnt(0)
	v_add_f32_e32 v62, v63, v74
	v_add_u32_e32 v63, -1, v114
	v_fma_f32 v74, -v63, v114, v103
	v_cmp_ge_f32_e64 s[6:7], 0, v74
	v_add_u32_e32 v74, 1, v114
	s_nop 0
	v_cndmask_b32_e64 v63, v114, v63, s[6:7]
	v_fma_f32 v114, -v74, v114, v103
	v_cmp_lt_f32_e64 s[6:7], 0, v114
	s_nop 1
	v_cndmask_b32_e64 v63, v63, v74, s[6:7]
	v_mul_f32_e32 v74, 0x37800000, v63
	v_cndmask_b32_e32 v63, v63, v74, vcc
	v_cmp_class_f32_e32 vcc, v103, v248
	s_nop 1
	v_cndmask_b32_e32 v74, v63, v103, vcc
	v_div_scale_f32 v103, s[6:7], v74, v74, 1.0
	v_rcp_f32_e32 v114, v103
	v_mov_b32_e32 v63, v62
	s_nop 1
	v_permlane32_swap_b32_e32 v62, v63
	v_fma_f32 v115, -v103, v114, 1.0
	v_fmac_f32_e32 v114, v115, v114
	v_div_scale_f32 v115, vcc, 1.0, v74, 1.0
	v_mul_f32_e32 v118, v115, v114
	v_fma_f32 v119, -v103, v118, v115
	v_fmac_f32_e32 v118, v119, v114
	v_fma_f32 v103, -v103, v118, v115
	v_div_fmas_f32 v103, v103, v114, v118
	v_div_fixup_f32 v74, v103, v74, 1.0
	s_and_saveexec_b64 s[6:7], s[4:5]
	s_cbranch_execz .LBB0_1561
	v_mov_b32_e32 v103, s13
	v_add_co_u32_e32 v118, vcc, 0x1fa00000, v103
	v_mov_b32_e32 v103, s11
	v_mul_f32_e32 v114, 0x3a800000, v165
	v_addc_co_u32_e32 v119, vcc, 0, v103, vcc
	v_mov_b32_e32 v115, v74
	global_store_dwordx2 v[118:119], v[114:115], off
